# grid barrier: non-leader workgroups spin on the cross-XCD release generation directly (one polling hop less)
# speedup vs baseline: 1.0038x; 1.0038x over previous
; __device__ __forceinline__ unsigned xb_ld(unsigned* p)              { return __hip_atomic_load(p, __ATOMIC_RELAXED, __HIP_MEMORY_SCOPE_AGENT); }
; __device__ __forceinline__ unsigned xb_add(unsigned* p, unsigned v) { return __hip_atomic_fetch_add(p, v, __ATOMIC_RELAXED, __HIP_MEMORY_SCOPE_AGENT); }
; #define XB_SPIN(cond, bar) do { unsigned _sp = 0; while (cond) { __builtin_amdgcn_s_sleep(1); \
;     if ((++_sp & 255u) == 0u) { if (xb_ld(&(bar)[XB_TMO])) break; if (_sp > XB_SPIN_CAP) { atomicAdd(&(bar)[XB_TMO], 1u); break; } } } } while (0)
; __device__ __forceinline__ void xcd_barrier(const XcdBarrier& b) {
;     ...
;         const unsigned old = xb_add(&bar[XB_XSUB(b.x)], 1u);
;         const unsigned gen = old / nloc;
;         if (old + 1u == (gen + 1u) * nloc) {
;             __builtin_amdgcn_fence(__ATOMIC_RELEASE, "agent");
;             asm volatile("s_waitcnt vmcnt(0)" ::: "memory");
;             const unsigned og = xb_add(&bar[XB_TOP], 1u);
;             const unsigned tg = og / nx;
;             if (og + 1u == (tg + 1u) * nx) xb_add(&bar[XB_TOPGEN], 1u);
;             else XB_SPIN(xb_ld(&bar[XB_TOPGEN]) == tg, bar);
;             __builtin_amdgcn_fence(__ATOMIC_ACQUIRE, "agent");
;             xb_add(&bar[XB_XGEN(b.x)], 1u);
;             asm volatile("s_waitcnt vmcnt(0)" ::: "memory");
;         } else {
;             XB_SPIN(xb_ld(&bar[XB_XGEN(b.x)]) == gen, bar);
.LBB0_58:
	s_or_b64 exec, exec, s[28:29]
	v_cvt_f32_u32_e32 v4, v2
	s_waitcnt vmcnt(0)
	v_readfirstlane_b32 s6, v3
	v_sub_u32_e32 v3, 0, v2
	v_rcp_iflag_f32_e32 v4, v4
	v_add_u32_e32 v5, s6, v1
	v_mul_f32_e32 v4, 0x4f7ffffe, v4
	v_cvt_u32_f32_e32 v4, v4
	v_mul_lo_u32 v1, v3, v4
	v_mul_hi_u32 v1, v4, v1
	v_add_u32_e32 v1, v4, v1
	v_mul_hi_u32 v1, v5, v1
	v_mul_lo_u32 v3, v1, v2
	v_sub_u32_e32 v3, v5, v3
	v_add_u32_e32 v4, 1, v1
	v_cmp_ge_u32_e32 vcc, v3, v2
	s_nop 1
	v_cndmask_b32_e32 v1, v1, v4, vcc
	v_sub_u32_e32 v4, v3, v2
	v_cndmask_b32_e32 v3, v3, v4, vcc
	v_add_u32_e32 v4, 1, v1
	v_cmp_ge_u32_e32 vcc, v3, v2
	v_add_u32_e32 v3, 1, v5
	s_nop 0
	v_cndmask_b32_e32 v1, v1, v4, vcc
	v_mul_lo_u32 v4, v2, v1
	v_add_u32_e32 v2, v4, v2
	v_cmp_ne_u32_e32 vcc, v3, v2
	s_and_saveexec_b64 s[6:7], vcc
	s_xor_b64 s[6:7], exec, s[6:7]
	s_cbranch_execz .LBB0_72
	s_waitcnt lgkmcnt(0)
	buffer_inv sc1
	v_mov_b32_e32 v0, 0x83500
	global_load_dword v0, v0, s[72:73] sc1
	s_add_u32 s38, s72, 0x83500
	s_addc_u32 s39, s73, 0
	s_waitcnt vmcnt(0)
	v_cmp_eq_u32_e32 vcc, v0, v1
	s_and_saveexec_b64 s[34:35], vcc
	s_cbranch_execz .LBB0_71
	s_add_u32 s36, s72, 0x80200
	s_addc_u32 s37, s73, 0
	s_mov_b32 s8, 1
	s_mov_b64 s[50:51], 0
	v_mov_b32_e32 v0, 0
	s_branch .LBB0_62

; __device__ __forceinline__ unsigned xb_ld(unsigned* p)              { return __hip_atomic_load(p, __ATOMIC_RELAXED, __HIP_MEMORY_SCOPE_AGENT); }
; __device__ __forceinline__ unsigned xb_add(unsigned* p, unsigned v) { return __hip_atomic_fetch_add(p, v, __ATOMIC_RELAXED, __HIP_MEMORY_SCOPE_AGENT); }
; #define XB_SPIN(cond, bar) do { unsigned _sp = 0; while (cond) { __builtin_amdgcn_s_sleep(1); \
;     if ((++_sp & 255u) == 0u) { if (xb_ld(&(bar)[XB_TMO])) break; if (_sp > XB_SPIN_CAP) { atomicAdd(&(bar)[XB_TMO], 1u); break; } } } } while (0)
; __device__ __forceinline__ void xcd_barrier(const XcdBarrier& b) {
;     ...
;         const unsigned old = xb_add(&bar[XB_XSUB(b.x)], 1u);
;         const unsigned gen = old / nloc;
;         if (old + 1u == (gen + 1u) * nloc) {
;             __builtin_amdgcn_fence(__ATOMIC_RELEASE, "agent");
;             asm volatile("s_waitcnt vmcnt(0)" ::: "memory");
;             const unsigned og = xb_add(&bar[XB_TOP], 1u);
;             const unsigned tg = og / nx;
;             if (og + 1u == (tg + 1u) * nx) xb_add(&bar[XB_TOPGEN], 1u);
;             else XB_SPIN(xb_ld(&bar[XB_TOPGEN]) == tg, bar);
;             __builtin_amdgcn_fence(__ATOMIC_ACQUIRE, "agent");
;             xb_add(&bar[XB_XGEN(b.x)], 1u);
;             asm volatile("s_waitcnt vmcnt(0)" ::: "memory");
;         } else {
;             XB_SPIN(xb_ld(&bar[XB_XGEN(b.x)]) == gen, bar);
.LBB0_197:
	s_or_b64 exec, exec, s[28:29]
	v_cvt_f32_u32_e32 v4, v2
	s_waitcnt vmcnt(0)
	v_readfirstlane_b32 s6, v3
	v_sub_u32_e32 v3, 0, v2
	v_rcp_iflag_f32_e32 v4, v4
	v_add_u32_e32 v5, s6, v1
	v_mul_f32_e32 v4, 0x4f7ffffe, v4
	v_cvt_u32_f32_e32 v4, v4
	v_mul_lo_u32 v1, v3, v4
	v_mul_hi_u32 v1, v4, v1
	v_add_u32_e32 v1, v4, v1
	v_mul_hi_u32 v1, v5, v1
	v_mul_lo_u32 v3, v1, v2
	v_sub_u32_e32 v3, v5, v3
	v_add_u32_e32 v4, 1, v1
	v_cmp_ge_u32_e32 vcc, v3, v2
	s_nop 1
	v_cndmask_b32_e32 v1, v1, v4, vcc
	v_sub_u32_e32 v4, v3, v2
	v_cndmask_b32_e32 v3, v3, v4, vcc
	v_add_u32_e32 v4, 1, v1
	v_cmp_ge_u32_e32 vcc, v3, v2
	v_add_u32_e32 v3, 1, v5
	s_nop 0
	v_cndmask_b32_e32 v1, v1, v4, vcc
	v_mul_lo_u32 v4, v2, v1
	v_add_u32_e32 v2, v4, v2
	v_cmp_ne_u32_e32 vcc, v3, v2
	s_and_saveexec_b64 s[6:7], vcc
	s_xor_b64 s[6:7], exec, s[6:7]
	s_cbranch_execz .LBB0_211
	s_waitcnt lgkmcnt(0)
	buffer_inv sc1
	v_mov_b32_e32 v0, 0x83500
	global_load_dword v0, v0, s[72:73] sc1
	s_add_u32 s62, s72, 0x83500
	s_addc_u32 s63, s73, 0
	s_waitcnt vmcnt(0)
	v_cmp_eq_u32_e32 vcc, v0, v1
	s_and_saveexec_b64 s[46:47], vcc
	s_cbranch_execz .LBB0_210
	s_add_u32 s50, s72, 0x80200
	s_addc_u32 s51, s73, 0
	s_mov_b32 s8, 1
	s_mov_b64 s[64:65], 0
	v_mov_b32_e32 v0, 0
	s_branch .LBB0_201

; __device__ __forceinline__ unsigned xb_ld(unsigned* p)              { return __hip_atomic_load(p, __ATOMIC_RELAXED, __HIP_MEMORY_SCOPE_AGENT); }
; __device__ __forceinline__ unsigned xb_add(unsigned* p, unsigned v) { return __hip_atomic_fetch_add(p, v, __ATOMIC_RELAXED, __HIP_MEMORY_SCOPE_AGENT); }
; #define XB_SPIN(cond, bar) do { unsigned _sp = 0; while (cond) { __builtin_amdgcn_s_sleep(1); \
;     if ((++_sp & 255u) == 0u) { if (xb_ld(&(bar)[XB_TMO])) break; if (_sp > XB_SPIN_CAP) { atomicAdd(&(bar)[XB_TMO], 1u); break; } } } } while (0)
; __device__ __forceinline__ void xcd_barrier(const XcdBarrier& b) {
;     ...
;         const unsigned old = xb_add(&bar[XB_XSUB(b.x)], 1u);
;         const unsigned gen = old / nloc;
;         if (old + 1u == (gen + 1u) * nloc) {
;             __builtin_amdgcn_fence(__ATOMIC_RELEASE, "agent");
;             asm volatile("s_waitcnt vmcnt(0)" ::: "memory");
;             const unsigned og = xb_add(&bar[XB_TOP], 1u);
;             const unsigned tg = og / nx;
;             if (og + 1u == (tg + 1u) * nx) xb_add(&bar[XB_TOPGEN], 1u);
;             else XB_SPIN(xb_ld(&bar[XB_TOPGEN]) == tg, bar);
;             __builtin_amdgcn_fence(__ATOMIC_ACQUIRE, "agent");
;             xb_add(&bar[XB_XGEN(b.x)], 1u);
;             asm volatile("s_waitcnt vmcnt(0)" ::: "memory");
;         } else {
;             XB_SPIN(xb_ld(&bar[XB_XGEN(b.x)]) == gen, bar);
.LBB0_332:
	s_or_b64 exec, exec, s[28:29]
	v_cvt_f32_u32_e32 v4, v2
	s_waitcnt vmcnt(0)
	v_readfirstlane_b32 s6, v3
	v_sub_u32_e32 v3, 0, v2
	v_rcp_iflag_f32_e32 v4, v4
	v_add_u32_e32 v5, s6, v1
	v_mul_f32_e32 v4, 0x4f7ffffe, v4
	v_cvt_u32_f32_e32 v4, v4
	v_mul_lo_u32 v1, v3, v4
	v_mul_hi_u32 v1, v4, v1
	v_add_u32_e32 v1, v4, v1
	v_mul_hi_u32 v1, v5, v1
	v_mul_lo_u32 v3, v1, v2
	v_sub_u32_e32 v3, v5, v3
	v_add_u32_e32 v4, 1, v1
	v_cmp_ge_u32_e32 vcc, v3, v2
	s_nop 1
	v_cndmask_b32_e32 v1, v1, v4, vcc
	v_sub_u32_e32 v4, v3, v2
	v_cndmask_b32_e32 v3, v3, v4, vcc
	v_add_u32_e32 v4, 1, v1
	v_cmp_ge_u32_e32 vcc, v3, v2
	v_add_u32_e32 v3, 1, v5
	s_nop 0
	v_cndmask_b32_e32 v1, v1, v4, vcc
	v_mul_lo_u32 v4, v2, v1
	v_add_u32_e32 v2, v4, v2
	v_cmp_ne_u32_e32 vcc, v3, v2
	s_and_saveexec_b64 s[6:7], vcc
	s_xor_b64 s[6:7], exec, s[6:7]
	s_cbranch_execz .LBB0_346
	s_waitcnt lgkmcnt(0)
	buffer_inv sc1
	v_mov_b32_e32 v0, 0x83500
	global_load_dword v0, v0, s[72:73] sc1
	s_add_u32 s50, s72, 0x83500
	s_addc_u32 s51, s73, 0
	s_waitcnt vmcnt(0)
	v_cmp_eq_u32_e32 vcc, v0, v1
	s_and_saveexec_b64 s[42:43], vcc
	s_cbranch_execz .LBB0_345
	s_add_u32 s46, s72, 0x80200
	s_addc_u32 s47, s73, 0
	s_mov_b32 s8, 1
	s_mov_b64 s[52:53], 0
	v_mov_b32_e32 v0, 0
	s_branch .LBB0_336

; __device__ __forceinline__ unsigned xb_ld(unsigned* p)              { return __hip_atomic_load(p, __ATOMIC_RELAXED, __HIP_MEMORY_SCOPE_AGENT); }
; __device__ __forceinline__ unsigned xb_add(unsigned* p, unsigned v) { return __hip_atomic_fetch_add(p, v, __ATOMIC_RELAXED, __HIP_MEMORY_SCOPE_AGENT); }
; #define XB_SPIN(cond, bar) do { unsigned _sp = 0; while (cond) { __builtin_amdgcn_s_sleep(1); \
;     if ((++_sp & 255u) == 0u) { if (xb_ld(&(bar)[XB_TMO])) break; if (_sp > XB_SPIN_CAP) { atomicAdd(&(bar)[XB_TMO], 1u); break; } } } } while (0)
; __device__ __forceinline__ void xcd_barrier(const XcdBarrier& b) {
;     ...
;         const unsigned old = xb_add(&bar[XB_XSUB(b.x)], 1u);
;         const unsigned gen = old / nloc;
;         if (old + 1u == (gen + 1u) * nloc) {
;             __builtin_amdgcn_fence(__ATOMIC_RELEASE, "agent");
;             asm volatile("s_waitcnt vmcnt(0)" ::: "memory");
;             const unsigned og = xb_add(&bar[XB_TOP], 1u);
;             const unsigned tg = og / nx;
;             if (og + 1u == (tg + 1u) * nx) xb_add(&bar[XB_TOPGEN], 1u);
;             else XB_SPIN(xb_ld(&bar[XB_TOPGEN]) == tg, bar);
;             __builtin_amdgcn_fence(__ATOMIC_ACQUIRE, "agent");
;             xb_add(&bar[XB_XGEN(b.x)], 1u);
;             asm volatile("s_waitcnt vmcnt(0)" ::: "memory");
;         } else {
;             XB_SPIN(xb_ld(&bar[XB_XGEN(b.x)]) == gen, bar);
.LBB0_429:
	s_or_b64 exec, exec, s[6:7]
	v_cvt_f32_u32_e32 v4, v2
	s_waitcnt vmcnt(0)
	v_readfirstlane_b32 s4, v3
	v_sub_u32_e32 v3, 0, v2
	v_rcp_iflag_f32_e32 v4, v4
	v_add_u32_e32 v5, s4, v1
	v_mul_f32_e32 v4, 0x4f7ffffe, v4
	v_cvt_u32_f32_e32 v4, v4
	v_mul_lo_u32 v1, v3, v4
	v_mul_hi_u32 v1, v4, v1
	v_add_u32_e32 v1, v4, v1
	v_mul_hi_u32 v1, v5, v1
	v_mul_lo_u32 v3, v1, v2
	v_sub_u32_e32 v3, v5, v3
	v_add_u32_e32 v4, 1, v1
	v_cmp_ge_u32_e32 vcc, v3, v2
	s_nop 1
	v_cndmask_b32_e32 v1, v1, v4, vcc
	v_sub_u32_e32 v4, v3, v2
	v_cndmask_b32_e32 v3, v3, v4, vcc
	v_add_u32_e32 v4, 1, v1
	v_cmp_ge_u32_e32 vcc, v3, v2
	v_add_u32_e32 v3, 1, v5
	s_nop 0
	v_cndmask_b32_e32 v1, v1, v4, vcc
	v_mul_lo_u32 v4, v2, v1
	v_add_u32_e32 v2, v4, v2
	v_cmp_ne_u32_e32 vcc, v3, v2
	s_and_saveexec_b64 s[4:5], vcc
	s_xor_b64 s[4:5], exec, s[4:5]
	s_cbranch_execz .LBB0_443
	s_waitcnt lgkmcnt(0)
	buffer_inv sc1
	v_mov_b32_e32 v0, 0x83500
	global_load_dword v0, v0, s[72:73] sc1
	s_add_u32 s46, s72, 0x83500
	s_addc_u32 s47, s73, 0
	s_waitcnt vmcnt(0)
	v_cmp_eq_u32_e32 vcc, v0, v1
	s_and_saveexec_b64 s[6:7], vcc
	s_cbranch_execz .LBB0_442
	s_add_u32 s40, s72, 0x80200
	s_addc_u32 s41, s73, 0
	s_mov_b32 s8, 1
	s_mov_b64 s[50:51], 0
	v_mov_b32_e32 v0, 0
	s_branch .LBB0_433

; __device__ __forceinline__ unsigned xb_ld(unsigned* p)              { return __hip_atomic_load(p, __ATOMIC_RELAXED, __HIP_MEMORY_SCOPE_AGENT); }
; __device__ __forceinline__ unsigned xb_add(unsigned* p, unsigned v) { return __hip_atomic_fetch_add(p, v, __ATOMIC_RELAXED, __HIP_MEMORY_SCOPE_AGENT); }
; #define XB_SPIN(cond, bar) do { unsigned _sp = 0; while (cond) { __builtin_amdgcn_s_sleep(1); \
;     if ((++_sp & 255u) == 0u) { if (xb_ld(&(bar)[XB_TMO])) break; if (_sp > XB_SPIN_CAP) { atomicAdd(&(bar)[XB_TMO], 1u); break; } } } } while (0)
; __device__ __forceinline__ void xcd_barrier(const XcdBarrier& b) {
;     ...
;         const unsigned old = xb_add(&bar[XB_XSUB(b.x)], 1u);
;         const unsigned gen = old / nloc;
;         if (old + 1u == (gen + 1u) * nloc) {
;             __builtin_amdgcn_fence(__ATOMIC_RELEASE, "agent");
;             asm volatile("s_waitcnt vmcnt(0)" ::: "memory");
;             const unsigned og = xb_add(&bar[XB_TOP], 1u);
;             const unsigned tg = og / nx;
;             if (og + 1u == (tg + 1u) * nx) xb_add(&bar[XB_TOPGEN], 1u);
;             else XB_SPIN(xb_ld(&bar[XB_TOPGEN]) == tg, bar);
;             __builtin_amdgcn_fence(__ATOMIC_ACQUIRE, "agent");
;             xb_add(&bar[XB_XGEN(b.x)], 1u);
;             asm volatile("s_waitcnt vmcnt(0)" ::: "memory");
;         } else {
;             XB_SPIN(xb_ld(&bar[XB_XGEN(b.x)]) == gen, bar);
;             __builtin_amdgcn_fence(__ATOMIC_ACQUIRE, "agent");
.LBB0_540:
	s_or_b64 exec, exec, s[12:13]
	v_cvt_f32_u32_e32 v4, v2
	s_waitcnt vmcnt(0)
	v_readfirstlane_b32 s6, v3
	v_sub_u32_e32 v3, 0, v2
	v_rcp_iflag_f32_e32 v4, v4
	v_add_u32_e32 v5, s6, v1
	v_mul_f32_e32 v4, 0x4f7ffffe, v4
	v_cvt_u32_f32_e32 v4, v4
	v_mul_lo_u32 v1, v3, v4
	v_mul_hi_u32 v1, v4, v1
	v_add_u32_e32 v1, v4, v1
	v_mul_hi_u32 v1, v5, v1
	v_mul_lo_u32 v3, v1, v2
	v_sub_u32_e32 v3, v5, v3
	v_add_u32_e32 v4, 1, v1
	v_cmp_ge_u32_e32 vcc, v3, v2
	s_nop 1
	v_cndmask_b32_e32 v1, v1, v4, vcc
	v_sub_u32_e32 v4, v3, v2
	v_cndmask_b32_e32 v3, v3, v4, vcc
	v_add_u32_e32 v4, 1, v1
	v_cmp_ge_u32_e32 vcc, v3, v2
	v_add_u32_e32 v3, 1, v5
	s_nop 0
	v_cndmask_b32_e32 v1, v1, v4, vcc
	v_mul_lo_u32 v4, v2, v1
	v_add_u32_e32 v2, v4, v2
	v_cmp_ne_u32_e32 vcc, v3, v2
	s_and_saveexec_b64 s[6:7], vcc
	s_xor_b64 s[6:7], exec, s[6:7]
	s_cbranch_execz .LBB0_554
	s_waitcnt lgkmcnt(0)
	buffer_inv sc1
	v_mov_b32_e32 v0, 0x83500
	global_load_dword v0, v0, s[72:73] sc1
	s_add_u32 s38, s72, 0x83500
	s_addc_u32 s39, s73, 0
	s_waitcnt vmcnt(0)
	v_cmp_eq_u32_e32 vcc, v0, v1
	s_and_saveexec_b64 s[12:13], vcc
	s_cbranch_execz .LBB0_553
	s_add_u32 s22, s72, 0x80200
	s_addc_u32 s23, s73, 0
	s_mov_b32 s8, 1
	s_mov_b64 s[42:43], 0
	v_mov_b32_e32 v0, 0
	s_branch .LBB0_544

; __device__ __forceinline__ unsigned xb_ld(unsigned* p)              { return __hip_atomic_load(p, __ATOMIC_RELAXED, __HIP_MEMORY_SCOPE_AGENT); }
; __device__ __forceinline__ unsigned xb_add(unsigned* p, unsigned v) { return __hip_atomic_fetch_add(p, v, __ATOMIC_RELAXED, __HIP_MEMORY_SCOPE_AGENT); }
; #define XB_SPIN(cond, bar) do { unsigned _sp = 0; while (cond) { __builtin_amdgcn_s_sleep(1); \
;     if ((++_sp & 255u) == 0u) { if (xb_ld(&(bar)[XB_TMO])) break; if (_sp > XB_SPIN_CAP) { atomicAdd(&(bar)[XB_TMO], 1u); break; } } } } while (0)
; __device__ __forceinline__ void xcd_barrier(const XcdBarrier& b) {
;     ...
;         const unsigned old = xb_add(&bar[XB_XSUB(b.x)], 1u);
;         const unsigned gen = old / nloc;
;         if (old + 1u == (gen + 1u) * nloc) {
;             __builtin_amdgcn_fence(__ATOMIC_RELEASE, "agent");
;             asm volatile("s_waitcnt vmcnt(0)" ::: "memory");
;             const unsigned og = xb_add(&bar[XB_TOP], 1u);
;             const unsigned tg = og / nx;
;             if (og + 1u == (tg + 1u) * nx) xb_add(&bar[XB_TOPGEN], 1u);
;             else XB_SPIN(xb_ld(&bar[XB_TOPGEN]) == tg, bar);
;             __builtin_amdgcn_fence(__ATOMIC_ACQUIRE, "agent");
;             xb_add(&bar[XB_XGEN(b.x)], 1u);
;             asm volatile("s_waitcnt vmcnt(0)" ::: "memory");
;         } else {
;             XB_SPIN(xb_ld(&bar[XB_XGEN(b.x)]) == gen, bar);
;             __builtin_amdgcn_fence(__ATOMIC_ACQUIRE, "agent");
.LBB0_637:
	s_or_b64 exec, exec, s[12:13]
	v_cvt_f32_u32_e32 v4, v2
	s_waitcnt vmcnt(0)
	v_readfirstlane_b32 s6, v3
	v_sub_u32_e32 v3, 0, v2
	v_rcp_iflag_f32_e32 v4, v4
	v_add_u32_e32 v5, s6, v1
	v_mul_f32_e32 v4, 0x4f7ffffe, v4
	v_cvt_u32_f32_e32 v4, v4
	v_mul_lo_u32 v1, v3, v4
	v_mul_hi_u32 v1, v4, v1
	v_add_u32_e32 v1, v4, v1
	v_mul_hi_u32 v1, v5, v1
	v_mul_lo_u32 v3, v1, v2
	v_sub_u32_e32 v3, v5, v3
	v_add_u32_e32 v4, 1, v1
	v_cmp_ge_u32_e32 vcc, v3, v2
	s_nop 1
	v_cndmask_b32_e32 v1, v1, v4, vcc
	v_sub_u32_e32 v4, v3, v2
	v_cndmask_b32_e32 v3, v3, v4, vcc
	v_add_u32_e32 v4, 1, v1
	v_cmp_ge_u32_e32 vcc, v3, v2
	v_add_u32_e32 v3, 1, v5
	s_nop 0
	v_cndmask_b32_e32 v1, v1, v4, vcc
	v_mul_lo_u32 v4, v2, v1
	v_add_u32_e32 v2, v4, v2
	v_cmp_ne_u32_e32 vcc, v3, v2
	s_and_saveexec_b64 s[6:7], vcc
	s_xor_b64 s[6:7], exec, s[6:7]
	s_cbranch_execz .LBB0_651
	s_waitcnt lgkmcnt(0)
	buffer_inv sc1
	v_mov_b32_e32 v0, 0x83500
	global_load_dword v0, v0, s[72:73] sc1
	s_add_u32 s40, s72, 0x83500
	s_addc_u32 s41, s73, 0
	s_waitcnt vmcnt(0)
	v_cmp_eq_u32_e32 vcc, v0, v1
	s_and_saveexec_b64 s[12:13], vcc
	s_cbranch_execz .LBB0_650
	s_add_u32 s22, s72, 0x80200
	s_addc_u32 s23, s73, 0
	s_mov_b32 s8, 1
	s_mov_b64 s[42:43], 0
	v_mov_b32_e32 v0, 0
	s_branch .LBB0_641

; __device__ __forceinline__ unsigned xb_ld(unsigned* p)              { return __hip_atomic_load(p, __ATOMIC_RELAXED, __HIP_MEMORY_SCOPE_AGENT); }
; __device__ __forceinline__ unsigned xb_add(unsigned* p, unsigned v) { return __hip_atomic_fetch_add(p, v, __ATOMIC_RELAXED, __HIP_MEMORY_SCOPE_AGENT); }
; #define XB_SPIN(cond, bar) do { unsigned _sp = 0; while (cond) { __builtin_amdgcn_s_sleep(1); \
;     if ((++_sp & 255u) == 0u) { if (xb_ld(&(bar)[XB_TMO])) break; if (_sp > XB_SPIN_CAP) { atomicAdd(&(bar)[XB_TMO], 1u); break; } } } } while (0)
; __device__ __forceinline__ void xcd_barrier(const XcdBarrier& b) {
;     ...
;         const unsigned old = xb_add(&bar[XB_XSUB(b.x)], 1u);
;         const unsigned gen = old / nloc;
;         if (old + 1u == (gen + 1u) * nloc) {
;             __builtin_amdgcn_fence(__ATOMIC_RELEASE, "agent");
;             asm volatile("s_waitcnt vmcnt(0)" ::: "memory");
;             const unsigned og = xb_add(&bar[XB_TOP], 1u);
;             const unsigned tg = og / nx;
;             if (og + 1u == (tg + 1u) * nx) xb_add(&bar[XB_TOPGEN], 1u);
;             else XB_SPIN(xb_ld(&bar[XB_TOPGEN]) == tg, bar);
;             __builtin_amdgcn_fence(__ATOMIC_ACQUIRE, "agent");
;             xb_add(&bar[XB_XGEN(b.x)], 1u);
;             asm volatile("s_waitcnt vmcnt(0)" ::: "memory");
;         } else {
;             XB_SPIN(xb_ld(&bar[XB_XGEN(b.x)]) == gen, bar);
;             __builtin_amdgcn_fence(__ATOMIC_ACQUIRE, "agent");
.LBB0_811:
	s_or_b64 exec, exec, s[24:25]
	v_cvt_f32_u32_e32 v4, v2
	s_waitcnt vmcnt(0)
	v_readfirstlane_b32 s6, v3
	v_sub_u32_e32 v3, 0, v2
	v_rcp_iflag_f32_e32 v4, v4
	v_add_u32_e32 v5, s6, v1
	v_mul_f32_e32 v4, 0x4f7ffffe, v4
	v_cvt_u32_f32_e32 v4, v4
	v_mul_lo_u32 v1, v3, v4
	v_mul_hi_u32 v1, v4, v1
	v_add_u32_e32 v1, v4, v1
	v_mul_hi_u32 v1, v5, v1
	v_mul_lo_u32 v3, v1, v2
	v_sub_u32_e32 v3, v5, v3
	v_add_u32_e32 v4, 1, v1
	v_cmp_ge_u32_e32 vcc, v3, v2
	s_nop 1
	v_cndmask_b32_e32 v1, v1, v4, vcc
	v_sub_u32_e32 v4, v3, v2
	v_cndmask_b32_e32 v3, v3, v4, vcc
	v_add_u32_e32 v4, 1, v1
	v_cmp_ge_u32_e32 vcc, v3, v2
	v_add_u32_e32 v3, 1, v5
	s_nop 0
	v_cndmask_b32_e32 v1, v1, v4, vcc
	v_mul_lo_u32 v4, v2, v1
	v_add_u32_e32 v2, v4, v2
	v_cmp_ne_u32_e32 vcc, v3, v2
	s_and_saveexec_b64 s[6:7], vcc
	s_xor_b64 s[6:7], exec, s[6:7]
	s_cbranch_execz .LBB0_825
	s_waitcnt lgkmcnt(0)
	buffer_inv sc1
	v_mov_b32_e32 v0, 0x83500
	global_load_dword v0, v0, s[72:73] sc1
	s_add_u32 s38, s72, 0x83500
	s_addc_u32 s39, s73, 0
	s_waitcnt vmcnt(0)
	v_cmp_eq_u32_e32 vcc, v0, v1
	s_and_saveexec_b64 s[24:25], vcc
	s_cbranch_execz .LBB0_824
	s_add_u32 s26, s72, 0x80200
	s_addc_u32 s27, s73, 0
	s_mov_b32 s8, 1
	s_mov_b64 s[40:41], 0
	v_mov_b32_e32 v0, 0
	s_branch .LBB0_815

; __device__ __forceinline__ unsigned xb_ld(unsigned* p)              { return __hip_atomic_load(p, __ATOMIC_RELAXED, __HIP_MEMORY_SCOPE_AGENT); }
; __device__ __forceinline__ unsigned xb_add(unsigned* p, unsigned v) { return __hip_atomic_fetch_add(p, v, __ATOMIC_RELAXED, __HIP_MEMORY_SCOPE_AGENT); }
; #define XB_SPIN(cond, bar) do { unsigned _sp = 0; while (cond) { __builtin_amdgcn_s_sleep(1); \
;     if ((++_sp & 255u) == 0u) { if (xb_ld(&(bar)[XB_TMO])) break; if (_sp > XB_SPIN_CAP) { atomicAdd(&(bar)[XB_TMO], 1u); break; } } } } while (0)
; __device__ __forceinline__ void xcd_barrier(const XcdBarrier& b) {
;     ...
;         const unsigned old = xb_add(&bar[XB_XSUB(b.x)], 1u);
;         const unsigned gen = old / nloc;
;         if (old + 1u == (gen + 1u) * nloc) {
;             __builtin_amdgcn_fence(__ATOMIC_RELEASE, "agent");
;             asm volatile("s_waitcnt vmcnt(0)" ::: "memory");
;             const unsigned og = xb_add(&bar[XB_TOP], 1u);
;             const unsigned tg = og / nx;
;             if (og + 1u == (tg + 1u) * nx) xb_add(&bar[XB_TOPGEN], 1u);
;             else XB_SPIN(xb_ld(&bar[XB_TOPGEN]) == tg, bar);
;             __builtin_amdgcn_fence(__ATOMIC_ACQUIRE, "agent");
;             xb_add(&bar[XB_XGEN(b.x)], 1u);
;             asm volatile("s_waitcnt vmcnt(0)" ::: "memory");
;         } else {
;             XB_SPIN(xb_ld(&bar[XB_XGEN(b.x)]) == gen, bar);
;             __builtin_amdgcn_fence(__ATOMIC_ACQUIRE, "agent");
.LBB0_1029:
	s_or_b64 exec, exec, s[14:15]
	v_cvt_f32_u32_e32 v4, v2
	s_waitcnt vmcnt(0)
	v_readfirstlane_b32 s6, v3
	v_sub_u32_e32 v3, 0, v2
	v_rcp_iflag_f32_e32 v4, v4
	v_add_u32_e32 v5, s6, v1
	v_mul_f32_e32 v4, 0x4f7ffffe, v4
	v_cvt_u32_f32_e32 v4, v4
	v_mul_lo_u32 v1, v3, v4
	v_mul_hi_u32 v1, v4, v1
	v_add_u32_e32 v1, v4, v1
	v_mul_hi_u32 v1, v5, v1
	v_mul_lo_u32 v3, v1, v2
	v_sub_u32_e32 v3, v5, v3
	v_add_u32_e32 v4, 1, v1
	v_cmp_ge_u32_e32 vcc, v3, v2
	s_nop 1
	v_cndmask_b32_e32 v1, v1, v4, vcc
	v_sub_u32_e32 v4, v3, v2
	v_cndmask_b32_e32 v3, v3, v4, vcc
	v_add_u32_e32 v4, 1, v1
	v_cmp_ge_u32_e32 vcc, v3, v2
	v_add_u32_e32 v3, 1, v5
	s_nop 0
	v_cndmask_b32_e32 v1, v1, v4, vcc
	v_mul_lo_u32 v4, v2, v1
	v_add_u32_e32 v2, v4, v2
	v_cmp_ne_u32_e32 vcc, v3, v2
	s_and_saveexec_b64 s[6:7], vcc
	s_xor_b64 s[6:7], exec, s[6:7]
	s_cbranch_execz .LBB0_1043
	s_waitcnt lgkmcnt(0)
	buffer_inv sc1
	v_mov_b32_e32 v0, 0x83500
	global_load_dword v0, v0, s[72:73] sc1
	s_add_u32 s18, s72, 0x83500
	s_addc_u32 s19, s73, 0
	s_waitcnt vmcnt(0)
	v_cmp_eq_u32_e32 vcc, v0, v1
	s_and_saveexec_b64 s[14:15], vcc
	s_cbranch_execz .LBB0_1042
	s_add_u32 s16, s72, 0x80200
	s_addc_u32 s17, s73, 0
	s_mov_b32 s8, 1
	s_mov_b64 s[20:21], 0
	v_mov_b32_e32 v0, 0
	s_branch .LBB0_1033

; __device__ __forceinline__ unsigned xb_ld(unsigned* p)              { return __hip_atomic_load(p, __ATOMIC_RELAXED, __HIP_MEMORY_SCOPE_AGENT); }
; __device__ __forceinline__ unsigned xb_add(unsigned* p, unsigned v) { return __hip_atomic_fetch_add(p, v, __ATOMIC_RELAXED, __HIP_MEMORY_SCOPE_AGENT); }
; #define XB_SPIN(cond, bar) do { unsigned _sp = 0; while (cond) { __builtin_amdgcn_s_sleep(1); \
;     if ((++_sp & 255u) == 0u) { if (xb_ld(&(bar)[XB_TMO])) break; if (_sp > XB_SPIN_CAP) { atomicAdd(&(bar)[XB_TMO], 1u); break; } } } } while (0)
; __device__ __forceinline__ void xcd_barrier(const XcdBarrier& b) {
;     ...
;         const unsigned old = xb_add(&bar[XB_XSUB(b.x)], 1u);
;         const unsigned gen = old / nloc;
;         if (old + 1u == (gen + 1u) * nloc) {
;             __builtin_amdgcn_fence(__ATOMIC_RELEASE, "agent");
;             asm volatile("s_waitcnt vmcnt(0)" ::: "memory");
;             const unsigned og = xb_add(&bar[XB_TOP], 1u);
;             const unsigned tg = og / nx;
;             if (og + 1u == (tg + 1u) * nx) xb_add(&bar[XB_TOPGEN], 1u);
;             else XB_SPIN(xb_ld(&bar[XB_TOPGEN]) == tg, bar);
;             __builtin_amdgcn_fence(__ATOMIC_ACQUIRE, "agent");
;             xb_add(&bar[XB_XGEN(b.x)], 1u);
;             asm volatile("s_waitcnt vmcnt(0)" ::: "memory");
;         } else {
;             XB_SPIN(xb_ld(&bar[XB_XGEN(b.x)]) == gen, bar);
;             __builtin_amdgcn_fence(__ATOMIC_ACQUIRE, "agent");
.LBB0_1349:
	s_or_b64 exec, exec, s[12:13]
	v_cvt_f32_u32_e32 v4, v2
	s_waitcnt vmcnt(0)
	v_readfirstlane_b32 s6, v3
	v_sub_u32_e32 v3, 0, v2
	v_rcp_iflag_f32_e32 v4, v4
	v_add_u32_e32 v5, s6, v1
	v_mul_f32_e32 v4, 0x4f7ffffe, v4
	v_cvt_u32_f32_e32 v4, v4
	v_mul_lo_u32 v1, v3, v4
	v_mul_hi_u32 v1, v4, v1
	v_add_u32_e32 v1, v4, v1
	v_mul_hi_u32 v1, v5, v1
	v_mul_lo_u32 v3, v1, v2
	v_sub_u32_e32 v3, v5, v3
	v_add_u32_e32 v4, 1, v1
	v_cmp_ge_u32_e32 vcc, v3, v2
	s_nop 1
	v_cndmask_b32_e32 v1, v1, v4, vcc
	v_sub_u32_e32 v4, v3, v2
	v_cndmask_b32_e32 v3, v3, v4, vcc
	v_add_u32_e32 v4, 1, v1
	v_cmp_ge_u32_e32 vcc, v3, v2
	v_add_u32_e32 v3, 1, v5
	s_nop 0
	v_cndmask_b32_e32 v1, v1, v4, vcc
	v_mul_lo_u32 v4, v2, v1
	v_add_u32_e32 v2, v4, v2
	v_cmp_ne_u32_e32 vcc, v3, v2
	s_and_saveexec_b64 s[6:7], vcc
	s_xor_b64 s[6:7], exec, s[6:7]
	s_cbranch_execz .LBB0_1363
	s_waitcnt lgkmcnt(0)
	buffer_inv sc1
	v_mov_b32_e32 v0, 0x83500
	global_load_dword v0, v0, s[72:73] sc1
	s_add_u32 s16, s72, 0x83500
	s_addc_u32 s17, s73, 0
	s_waitcnt vmcnt(0)
	v_cmp_eq_u32_e32 vcc, v0, v1
	s_and_saveexec_b64 s[12:13], vcc
	s_cbranch_execz .LBB0_1362
	s_add_u32 s14, s72, 0x80200
	s_addc_u32 s15, s73, 0
	s_mov_b32 s8, 1
	s_mov_b64 s[18:19], 0
	v_mov_b32_e32 v0, 0
	s_branch .LBB0_1353
